# v95 + ph_win: hand-written EpiZ epilogue for non-rope tiles with row scales cached across consecutive tiles of the same row block
# speedup vs baseline: 1.0050x; 1.0039x over previous
;     DI bool next(int i, Unit& u) const {
;         const long L = (long)i * G + c; if (L >= nwg) return false;
;         int wgid = (int)L; { const int q = nwg / NXCD, r = nwg % NXCD, xcd = wgid % NXCD, off = wgid / NXCD; wgid = (xcd < r ? xcd * (q + 1) : r * (q + 1) + (xcd - r) * q) + off; }
;         const int nig = WGM * nN, gid = wgid / nig, fm = gid * WGM, gsz = (nM - fm) < WGM ? (nM - fm) : WGM;
;         u.pm = fm + ((wgid % nig) % gsz); u.pn = (wgid % nig) / gsz; return true;
; template <class Epi>
; DI void gemm_phase(LAS unsigned char* lds, const Gemm g, const StaticOrder& S, const Epi& E) {
;     ...
;         const bool has_next = S.next(ui + 1, nxt);
.Lwin_again:
	s_mov_b32 s101, -1
	v_writelane_b32 v255, s101, 24
	s_waitcnt lgkmcnt(0)
	s_mov_b64 s[4:5], s[0:1]
	s_add_i32 s12, s2, s100
	v_mov_b32_e32 v10, v242
	s_cmpk_lt_i32 s12, 0x980
	s_cselect_b64 s[8:9], -1, 0
	s_cmpk_gt_i32 s12, 0x97f
	v_readfirstlane_b32 s17, v10
	s_cbranch_scc1 .LBB0_83
	s_ashr_i32 s6, s12, 31
	s_lshr_b32 s6, s6, 29
	s_add_i32 s6, s12, s6
	s_ashr_i32 s7, s6, 3
	s_and_b32 s6, s6, -8
	s_sub_i32 s6, s12, s6
	s_cmp_lt_i32 s6, 0
	s_cselect_b32 s18, s74, 0x130
	s_mul_i32 s6, s18, s6
	s_add_i32 s6, s6, s7
	s_mul_hi_i32 s7, s6, 0x6bca1af3
	s_lshr_b32 s18, s7, 31
	s_ashr_i32 s7, s7, 6
	s_add_i32 s7, s7, s18
	s_lshl_b32 s18, s7, 2
	s_mulk_i32 s7, 0x98
	s_sub_i32 s6, s6, s7
	s_bfe_u32 s7, s6, 0x2001d
	s_add_i32 s7, s6, s7
	s_sext_i32_i16 s19, s7
	s_and_b32 s7, s7, 0xfffc
	s_sub_i32 s6, s6, s7
	s_sext_i32_i16 s6, s6
	s_add_i32 s6, s18, s6
	s_ashr_i32 s60, s19, 2

;     DI void operator()(const f32x4 (&acc)[2][2][4][2], const Unit& u, int wr, int wc, int fr, int fq) const {
;         const int col0 = u.pn * BM + wc * 32 + 8 * fq;
;         const bool rope = u.pn < 4; const float ksc = (u.pn >= 2) ? 0.08838834764831845f : 1.0f;
;         const int fi = 4 * (4 * wc + fq);
;         const int rowb = u.pm * BM + wr * 64 + fr;
;         f32x4 sl[2][4];
; #pragma unroll
;         for (int ai = 0; ai < 2; ++ai)
; #pragma unroll
;             for (int m = 0; m < 4; ++m) sl[ai][m] = *(const f32x4*)(slots + (size_t)(rowb + ai * HALF + m * 16) * 16 + 4 * fq);
;         asm volatile("" ::: "memory");
; #pragma unroll
;         for (int ai = 0; ai < 2; ++ai) {
;             f32x4 c4[4], s4[4];
; #pragma unroll
;             for (int m = 0; m < 4; ++m) { c4[m] = (f32x4){1.f, 1.f, 1.f, 1.f}; s4[m] = (f32x4){0.f, 0.f, 0.f, 0.f}; }
;             if (rope) {
; #pragma unroll
;                 for (int m = 0; m < 4; ++m) { const int pos = (rowb + ai * HALF + m * 16) & (SEQ - 1); c4[m] = *(const f32x4*)(cs + pos * 64 + fi); s4[m] = *(const f32x4*)(sn + pos * 64 + fi); }
.LBB0_95:
	s_cmp_gt_i32 s60, 3
	s_cbranch_scc1 .Lwin_fast
	s_mov_b32 s101, -1
	v_writelane_b32 v255, s101, 24
	v_lshl_add_u32 v238, s6, 8, v1
	v_or_b32_e32 v236, 16, v238
	v_ashrrev_i32_e32 v239, 31, v238
	v_ashrrev_i32_e32 v237, 31, v236
	v_lshlrev_b64 v[66:67], 6, v[238:239]
	v_lshlrev_b64 v[68:69], 6, v[236:237]
	v_or_b32_e32 v234, 32, v238
	v_or_b32_e32 v232, 48, v238
	v_lshl_add_u64 v[66:67], v[214:215], 0, v[66:67]
	v_lshl_add_u64 v[68:69], v[214:215], 0, v[68:69]
	v_ashrrev_i32_e32 v235, 31, v234
	v_ashrrev_i32_e32 v233, 31, v232
	global_load_dwordx4 v[190:193], v[66:67], off
	global_load_dwordx4 v[178:181], v[68:69], off
	v_lshlrev_b64 v[66:67], 6, v[234:235]
	v_lshlrev_b64 v[68:69], 6, v[232:233]
	v_add_u32_e32 v230, 0x80, v238
	v_add_u32_e32 v228, 0x90, v238
	v_lshl_add_u64 v[66:67], v[214:215], 0, v[66:67]
	v_lshl_add_u64 v[68:69], v[214:215], 0, v[68:69]
	v_ashrrev_i32_e32 v231, 31, v230
	v_ashrrev_i32_e32 v229, 31, v228
	global_load_dwordx4 v[166:169], v[66:67], off
	global_load_dwordx4 v[154:157], v[68:69], off
	v_lshlrev_b64 v[66:67], 6, v[230:231]
	v_lshlrev_b64 v[68:69], 6, v[228:229]
	v_add_u32_e32 v226, 0xa0, v238
	v_add_u32_e32 v224, 0xb0, v238
	v_lshl_add_u64 v[66:67], v[214:215], 0, v[66:67]
	v_lshl_add_u64 v[68:69], v[214:215], 0, v[68:69]
	v_ashrrev_i32_e32 v227, 31, v226
	v_ashrrev_i32_e32 v225, 31, v224
	global_load_dwordx4 v[118:121], v[66:67], off
	global_load_dwordx4 v[98:101], v[68:69], off
	v_lshlrev_b64 v[66:67], 6, v[226:227]
	v_lshlrev_b64 v[68:69], 6, v[224:225]
	v_lshl_add_u64 v[66:67], v[214:215], 0, v[66:67]
	v_lshl_add_u64 v[68:69], v[214:215], 0, v[68:69]
	global_load_dwordx4 v[78:81], v[66:67], off
	s_nop 0
	global_load_dwordx4 v[66:69], v[68:69], off
	s_cmp_lt_i32 s60, 4
	s_cselect_b64 s[62:63], -1, 0
	s_cmp_gt_i32 s60, 3
	v_lshlrev_b32_e32 v229, 6, v238
	s_cbranch_scc1 .LBB0_97
	v_lshlrev_b32_e32 v138, 2, v229
	v_and_b32_e32 v138, 0xfcf00, v138
	v_mov_b32_e32 v139, v0
	v_lshl_add_u64 v[140:141], v[216:217], 0, v[138:139]
	v_lshl_add_u64 v[142:143], v[218:219], 0, v[138:139]
	global_load_dwordx4 v[186:189], v[140:141], off
	global_load_dwordx4 v[182:185], v[142:143], off
	v_or_b32_e32 v140, 0x1000, v138
	v_mov_b32_e32 v141, v0
	v_lshl_add_u64 v[142:143], v[216:217], 0, v[140:141]
	v_lshl_add_u64 v[140:141], v[218:219], 0, v[140:141]
	global_load_dwordx4 v[174:177], v[142:143], off
	global_load_dwordx4 v[170:173], v[140:141], off
	v_or_b32_e32 v140, 0x2000, v138
	v_mov_b32_e32 v141, v0
	v_lshl_add_u64 v[142:143], v[216:217], 0, v[140:141]
	v_lshl_add_u64 v[140:141], v[218:219], 0, v[140:141]
	v_or_b32_e32 v138, 0x3000, v138
	global_load_dwordx4 v[162:165], v[142:143], off
	global_load_dwordx4 v[158:161], v[140:141], off
	v_lshl_add_u64 v[140:141], v[216:217], 0, v[138:139]
	v_lshl_add_u64 v[138:139], v[218:219], 0, v[138:139]
	global_load_dwordx4 v[142:145], v[140:141], off
	s_nop 0
	global_load_dwordx4 v[138:141], v[138:139], off
	s_branch .LBB0_98

; template <class Epi>
; DI void gemm_phase(LAS unsigned char* lds, const Gemm g, const StaticOrder& S, const Epi& E) {
;     ...
;         if (wr == 0) PG8_BAR;
;         E(acc, cur, wr, wc, fr, fq);
;         if (!has_next) break;
; #pragma unroll
;         for (int a = 0; a < 2; ++a)
; #pragma unroll
;             for (int b = 0; b < 2; ++b)
; #pragma unroll
;     DI void operator()(const f32x4 (&acc)[2][2][4][2], const Unit& u, int wr, int wc, int fr, int fq) const {
;         const int col0 = u.pn * BM + wc * 32 + 8 * fq;
;         const bool rope = u.pn < 4; const float ksc = (u.pn >= 2) ? 0.08838834764831845f : 1.0f;
;         const int fi = 4 * (4 * wc + fq);
;         const int rowb = u.pm * BM + wr * 64 + fr;
;         f32x4 sl[2][4];
; #pragma unroll
;         for (int ai = 0; ai < 2; ++ai)
; #pragma unroll
;             for (int m = 0; m < 4; ++m) sl[ai][m] = *(const f32x4*)(slots + (size_t)(rowb + ai * HALF + m * 16) * 16 + 4 * fq);
;         asm volatile("" ::: "memory");
; #pragma unroll
;         for (int ai = 0; ai < 2; ++ai) {
;             f32x4 c4[4], s4[4];
; #pragma unroll
;             for (int m = 0; m < 4; ++m) { c4[m] = (f32x4){1.f, 1.f, 1.f, 1.f}; s4[m] = (f32x4){0.f, 0.f, 0.f, 0.f}; }
;             if (rope) {
; #pragma unroll
;                 for (int m = 0; m < 4; ++m) { const int pos = (rowb + ai * HALF + m * 16) & (SEQ - 1); c4[m] = *(const f32x4*)(cs + pos * 64 + fi); s4[m] = *(const f32x4*)(sn + pos * 64 + fi); }
;             }
;             asm volatile("" ::: "memory");
; #pragma unroll
;             for (int m = 0; m < 4; ++m) {
;                 const int row = rowb + ai * HALF + m * 16;
;                 float t = (sl[ai][m][0] + sl[ai][m][1]) + (sl[ai][m][2] + sl[ai][m][3]);
;                 t += __shfl_xor(t, 16); t += __shfl_xor(t, 32);
;                 const float rs = __builtin_amdgcn_rsqf(t * (1.0f / D) + EPS);
; #pragma unroll
;                 for (int bj = 0; bj < 2; ++bj) {
;                     f32x4 v0 = acc[ai][bj][m][0] * rs, v1 = acc[ai][bj][m][1] * rs;
;                     if (rope) { const f32x4 o0 = (v0 * c4[m] - v1 * s4[m]) * ksc, o1 = (v0 * s4[m] + v1 * c4[m]) * ksc; v0 = o0; v1 = o1; }
;                     u32x4 w; w.x = pk2(v0[0], v0[1]); w.y = pk2(v0[2], v0[3]); w.z = pk2(v1[0], v1[1]); w.w = pk2(v1[2], v1[3]);
;                     *(u32x4*)(Z + (size_t)row * INW + col0 + bj * HALF) = w;
.Lwin_epi_done:
	s_andn2_b64 vcc, exec, s[4:5]
	s_mov_b64 s[4:5], -1
	s_cbranch_vccnz .LBB0_88
	s_andn2_b64 vcc, exec, s[8:9]
	s_cbranch_vccnz .LBB0_87
	s_barrier
	s_branch .LBB0_87
.Lwin_fast:
	v_lshl_add_u32 v228, s6, 8, v1
	v_lshl_or_b32 v202, s60, 8, v254
	v_mul_lo_u32 v203, v228, s78
	v_readlane_b32 s101, v255, 24
	v_lshl_add_u32 v138, v202, 1, v203
	v_add_u32_e32 v139, 0x4c000, v138
	v_add_u32_e32 v140, 0x98000, v138
	v_add_u32_e32 v141, 0xe4000, v138
	v_add_u32_e32 v142, 0x260000, v138
	v_add_u32_e32 v143, 0x2ac000, v138
	v_add_u32_e32 v144, 0x2f8000, v138
	v_add_u32_e32 v145, 0x344000, v138
	s_cmp_eq_u32 s101, s6
	s_cbranch_scc1 .Lwin_rs_cached
	v_lshlrev_b32_e32 v224, 6, v228
	v_mov_b32_e32 v225, 0
	v_add_u32_e32 v226, 0x2000, v224
	v_mov_b32_e32 v227, 0
	v_lshl_add_u64 v[224:225], v[214:215], 0, v[224:225]
	v_lshl_add_u64 v[226:227], v[214:215], 0, v[226:227]
	global_load_dwordx4 v[162:165], v[224:225], off
	global_load_dwordx4 v[166:169], v[224:225], off offset:1024
	global_load_dwordx4 v[170:173], v[224:225], off offset:2048
	global_load_dwordx4 v[174:177], v[224:225], off offset:3072
	global_load_dwordx4 v[178:181], v[226:227], off
	global_load_dwordx4 v[182:185], v[226:227], off offset:1024
	global_load_dwordx4 v[186:189], v[226:227], off offset:2048
	global_load_dwordx4 v[190:193], v[226:227], off offset:3072
	v_xor_b32_e32 v200, 16, v249
	v_xor_b32_e32 v201, 32, v249
	v_lshlrev_b32_e32 v200, 2, v200
	v_lshlrev_b32_e32 v201, 2, v201
	v_writelane_b32 v255, s6, 24
	s_waitcnt vmcnt(7)
	v_add_f32_e32 v162, v162, v163
	v_add_f32_e32 v164, v164, v165
	v_add_f32_e32 v162, v162, v164
	ds_bpermute_b32 v163, v200, v162
	s_waitcnt vmcnt(6)
	v_add_f32_e32 v166, v166, v167
	v_add_f32_e32 v168, v168, v169
	v_add_f32_e32 v166, v166, v168
	ds_bpermute_b32 v167, v200, v166
	s_waitcnt vmcnt(5)
	v_add_f32_e32 v170, v170, v171
	v_add_f32_e32 v172, v172, v173
	v_add_f32_e32 v170, v170, v172
	ds_bpermute_b32 v171, v200, v170
	s_waitcnt vmcnt(4)
	v_add_f32_e32 v174, v174, v175
	v_add_f32_e32 v176, v176, v177
	v_add_f32_e32 v174, v174, v176
	ds_bpermute_b32 v175, v200, v174
	s_waitcnt vmcnt(3)
	v_add_f32_e32 v178, v178, v179
	v_add_f32_e32 v180, v180, v181
	v_add_f32_e32 v178, v178, v180
	ds_bpermute_b32 v179, v200, v178
	s_waitcnt vmcnt(2)
	v_add_f32_e32 v182, v182, v183
	v_add_f32_e32 v184, v184, v185
	v_add_f32_e32 v182, v182, v184
	ds_bpermute_b32 v183, v200, v182
	s_waitcnt vmcnt(1)
	v_add_f32_e32 v186, v186, v187
	v_add_f32_e32 v188, v188, v189
	v_add_f32_e32 v186, v186, v188
	ds_bpermute_b32 v187, v200, v186
	s_waitcnt vmcnt(0)
	v_add_f32_e32 v190, v190, v191
	v_add_f32_e32 v192, v192, v193
	v_add_f32_e32 v190, v190, v192
	ds_bpermute_b32 v191, v200, v190
	s_waitcnt lgkmcnt(0)
	v_add_f32_e32 v162, v162, v163
	ds_bpermute_b32 v163, v201, v162
	v_add_f32_e32 v166, v166, v167
	ds_bpermute_b32 v167, v201, v166
	v_add_f32_e32 v170, v170, v171
	ds_bpermute_b32 v171, v201, v170
	v_add_f32_e32 v174, v174, v175
	ds_bpermute_b32 v175, v201, v174
	v_add_f32_e32 v178, v178, v179
	ds_bpermute_b32 v179, v201, v178
	v_add_f32_e32 v182, v182, v183
	ds_bpermute_b32 v183, v201, v182
	v_add_f32_e32 v186, v186, v187
	ds_bpermute_b32 v187, v201, v186
	v_add_f32_e32 v190, v190, v191
	ds_bpermute_b32 v191, v201, v190
	s_waitcnt lgkmcnt(0)
	v_add_f32_e32 v162, v162, v163
	v_add_f32_e32 v166, v166, v167
	v_add_f32_e32 v170, v170, v171
	v_add_f32_e32 v174, v174, v175
	v_add_f32_e32 v178, v178, v179
	v_add_f32_e32 v182, v182, v183
	v_add_f32_e32 v186, v186, v187
	v_add_f32_e32 v190, v190, v191
	v_fmamk_f32 v162, v162, 0x3a800000, v243
	v_fmamk_f32 v166, v166, 0x3a800000, v243
	v_fmamk_f32 v170, v170, 0x3a800000, v243
	v_fmamk_f32 v174, v174, 0x3a800000, v243
	v_fmamk_f32 v178, v178, 0x3a800000, v243
	v_fmamk_f32 v182, v182, 0x3a800000, v243
	v_fmamk_f32 v186, v186, 0x3a800000, v243
	v_fmamk_f32 v190, v190, 0x3a800000, v243
	v_rsq_f32_e32 v204, v162
	v_rsq_f32_e32 v205, v166
	v_rsq_f32_e32 v230, v170
	v_rsq_f32_e32 v231, v174
	v_rsq_f32_e32 v233, v178
	v_rsq_f32_e32 v235, v182
	v_rsq_f32_e32 v240, v186
	v_rsq_f32_e32 v241, v190
	s_nop 1
.Lwin_rs_cached:
	v_pk_mul_f32 v[150:151], v[150:151], v[204:205] op_sel_hi:[1,0]
	v_pk_mul_f32 v[152:153], v[152:153], v[204:205] op_sel_hi:[1,0]
	v_pk_mul_f32 v[146:147], v[146:147], v[204:205] op_sel_hi:[1,0]
	v_pk_mul_f32 v[148:149], v[148:149], v[204:205] op_sel_hi:[1,0]
	v_cvt_pk_bf16_f32 v66, v150, v151
	v_cvt_pk_bf16_f32 v67, v152, v153
	v_cvt_pk_bf16_f32 v68, v146, v147
	v_cvt_pk_bf16_f32 v69, v148, v149
	global_store_dwordx4 v138, v[66:69], s[48:49]
	v_pk_mul_f32 v[134:135], v[134:135], v[204:205] op_sel_hi:[1,0]
	v_pk_mul_f32 v[136:137], v[136:137], v[204:205] op_sel_hi:[1,0]
	v_pk_mul_f32 v[130:131], v[130:131], v[204:205] op_sel_hi:[1,0]
	v_pk_mul_f32 v[132:133], v[132:133], v[204:205] op_sel_hi:[1,0]
	v_cvt_pk_bf16_f32 v78, v134, v135
	v_cvt_pk_bf16_f32 v79, v136, v137
	v_cvt_pk_bf16_f32 v80, v130, v131
	v_cvt_pk_bf16_f32 v81, v132, v133
	global_store_dwordx4 v138, v[78:81], s[48:49] offset:256
	v_pk_mul_f32 v[126:127], v[126:127], v[204:205] op_sel:[0,1] op_sel_hi:[1,1]
	v_pk_mul_f32 v[128:129], v[128:129], v[204:205] op_sel:[0,1] op_sel_hi:[1,1]
	v_pk_mul_f32 v[122:123], v[122:123], v[204:205] op_sel:[0,1] op_sel_hi:[1,1]
	v_pk_mul_f32 v[124:125], v[124:125], v[204:205] op_sel:[0,1] op_sel_hi:[1,1]
	v_cvt_pk_bf16_f32 v98, v126, v127
	v_cvt_pk_bf16_f32 v99, v128, v129
	v_cvt_pk_bf16_f32 v100, v122, v123
	v_cvt_pk_bf16_f32 v101, v124, v125
	global_store_dwordx4 v139, v[98:101], s[48:49]
	v_pk_mul_f32 v[114:115], v[114:115], v[204:205] op_sel:[0,1] op_sel_hi:[1,1]
	v_pk_mul_f32 v[116:117], v[116:117], v[204:205] op_sel:[0,1] op_sel_hi:[1,1]
; DI unsigned pk2(float lo, float hi) { unsigned r; asm("v_cvt_pk_bf16_f32 %0, %1, %2" : "=v"(r) : "v"(lo), "v"(hi)); return r; }
;     DI void operator()(const f32x4 (&acc)[2][2][4][2], const Unit& u, int wr, int wc, int fr, int fq) const {
;     ...
;             for (int m = 0; m < 4; ++m) {
;                 const int row = rowb + ai * HALF + m * 16;
;                 float t = (sl[ai][m][0] + sl[ai][m][1]) + (sl[ai][m][2] + sl[ai][m][3]);
;                 t += __shfl_xor(t, 16); t += __shfl_xor(t, 32);
;                 const float rs = __builtin_amdgcn_rsqf(t * (1.0f / D) + EPS);
; #pragma unroll
;                 for (int bj = 0; bj < 2; ++bj) {
;                     f32x4 v0 = acc[ai][bj][m][0] * rs, v1 = acc[ai][bj][m][1] * rs;
;                     if (rope) { const f32x4 o0 = (v0 * c4[m] - v1 * s4[m]) * ksc, o1 = (v0 * s4[m] + v1 * c4[m]) * ksc; v0 = o0; v1 = o1; }
;                     u32x4 w; w.x = pk2(v0[0], v0[1]); w.y = pk2(v0[2], v0[3]); w.z = pk2(v1[0], v1[1]); w.w = pk2(v1[2], v1[3]);
;                     *(u32x4*)(Z + (size_t)row * INW + col0 + bj * HALF) = w;
;                 }
;             }
	v_pk_mul_f32 v[110:111], v[110:111], v[204:205] op_sel:[0,1] op_sel_hi:[1,1]
	v_pk_mul_f32 v[112:113], v[112:113], v[204:205] op_sel:[0,1] op_sel_hi:[1,1]
	v_cvt_pk_bf16_f32 v118, v114, v115
	v_cvt_pk_bf16_f32 v119, v116, v117
	v_cvt_pk_bf16_f32 v120, v110, v111
	v_cvt_pk_bf16_f32 v121, v112, v113
	global_store_dwordx4 v139, v[118:121], s[48:49] offset:256
	v_pk_mul_f32 v[106:107], v[106:107], v[230:231] op_sel_hi:[1,0]
	v_pk_mul_f32 v[108:109], v[108:109], v[230:231] op_sel_hi:[1,0]
	v_pk_mul_f32 v[102:103], v[102:103], v[230:231] op_sel_hi:[1,0]
	v_pk_mul_f32 v[104:105], v[104:105], v[230:231] op_sel_hi:[1,0]
	v_cvt_pk_bf16_f32 v66, v106, v107
	v_cvt_pk_bf16_f32 v67, v108, v109
	v_cvt_pk_bf16_f32 v68, v102, v103
	v_cvt_pk_bf16_f32 v69, v104, v105
	global_store_dwordx4 v140, v[66:69], s[48:49]
	v_pk_mul_f32 v[94:95], v[94:95], v[230:231] op_sel_hi:[1,0]
	v_pk_mul_f32 v[96:97], v[96:97], v[230:231] op_sel_hi:[1,0]
	v_pk_mul_f32 v[90:91], v[90:91], v[230:231] op_sel_hi:[1,0]
	v_pk_mul_f32 v[92:93], v[92:93], v[230:231] op_sel_hi:[1,0]
	v_cvt_pk_bf16_f32 v78, v94, v95
	v_cvt_pk_bf16_f32 v79, v96, v97
	v_cvt_pk_bf16_f32 v80, v90, v91
	v_cvt_pk_bf16_f32 v81, v92, v93
	global_store_dwordx4 v140, v[78:81], s[48:49] offset:256
	v_pk_mul_f32 v[86:87], v[86:87], v[230:231] op_sel:[0,1] op_sel_hi:[1,1]
	v_pk_mul_f32 v[88:89], v[88:89], v[230:231] op_sel:[0,1] op_sel_hi:[1,1]
	v_pk_mul_f32 v[82:83], v[82:83], v[230:231] op_sel:[0,1] op_sel_hi:[1,1]
	v_pk_mul_f32 v[84:85], v[84:85], v[230:231] op_sel:[0,1] op_sel_hi:[1,1]
	v_cvt_pk_bf16_f32 v98, v86, v87
	v_cvt_pk_bf16_f32 v99, v88, v89
	v_cvt_pk_bf16_f32 v100, v82, v83
	v_cvt_pk_bf16_f32 v101, v84, v85
	global_store_dwordx4 v141, v[98:101], s[48:49]
	v_pk_mul_f32 v[74:75], v[74:75], v[230:231] op_sel:[0,1] op_sel_hi:[1,1]
	v_pk_mul_f32 v[76:77], v[76:77], v[230:231] op_sel:[0,1] op_sel_hi:[1,1]
	v_pk_mul_f32 v[70:71], v[70:71], v[230:231] op_sel:[0,1] op_sel_hi:[1,1]
	v_pk_mul_f32 v[72:73], v[72:73], v[230:231] op_sel:[0,1] op_sel_hi:[1,1]
	v_cvt_pk_bf16_f32 v118, v74, v75
	v_cvt_pk_bf16_f32 v119, v76, v77
	v_cvt_pk_bf16_f32 v120, v70, v71
	v_cvt_pk_bf16_f32 v121, v72, v73
	global_store_dwordx4 v141, v[118:121], s[48:49] offset:256
	v_pk_mul_f32 v[62:63], v[62:63], v[232:233] op_sel:[0,1] op_sel_hi:[1,1]
	v_pk_mul_f32 v[64:65], v[64:65], v[232:233] op_sel:[0,1] op_sel_hi:[1,1]
	v_pk_mul_f32 v[58:59], v[58:59], v[232:233] op_sel:[0,1] op_sel_hi:[1,1]
	v_pk_mul_f32 v[60:61], v[60:61], v[232:233] op_sel:[0,1] op_sel_hi:[1,1]
	v_cvt_pk_bf16_f32 v66, v62, v63
	v_cvt_pk_bf16_f32 v67, v64, v65
	v_cvt_pk_bf16_f32 v68, v58, v59
	v_cvt_pk_bf16_f32 v69, v60, v61
	global_store_dwordx4 v142, v[66:69], s[48:49]
	v_pk_mul_f32 v[54:55], v[54:55], v[232:233] op_sel:[0,1] op_sel_hi:[1,1]
	v_pk_mul_f32 v[56:57], v[56:57], v[232:233] op_sel:[0,1] op_sel_hi:[1,1]
	v_pk_mul_f32 v[50:51], v[50:51], v[232:233] op_sel:[0,1] op_sel_hi:[1,1]
	v_pk_mul_f32 v[52:53], v[52:53], v[232:233] op_sel:[0,1] op_sel_hi:[1,1]
	v_cvt_pk_bf16_f32 v78, v54, v55
	v_cvt_pk_bf16_f32 v79, v56, v57
	v_cvt_pk_bf16_f32 v80, v50, v51
	v_cvt_pk_bf16_f32 v81, v52, v53
	global_store_dwordx4 v142, v[78:81], s[48:49] offset:256
	v_pk_mul_f32 v[46:47], v[46:47], v[234:235] op_sel:[0,1] op_sel_hi:[1,1]
	v_pk_mul_f32 v[48:49], v[48:49], v[234:235] op_sel:[0,1] op_sel_hi:[1,1]
	v_pk_mul_f32 v[42:43], v[42:43], v[234:235] op_sel:[0,1] op_sel_hi:[1,1]
	v_pk_mul_f32 v[44:45], v[44:45], v[234:235] op_sel:[0,1] op_sel_hi:[1,1]
	v_cvt_pk_bf16_f32 v98, v46, v47
	v_cvt_pk_bf16_f32 v99, v48, v49
	v_cvt_pk_bf16_f32 v100, v42, v43
	v_cvt_pk_bf16_f32 v101, v44, v45
	global_store_dwordx4 v143, v[98:101], s[48:49]
	v_pk_mul_f32 v[38:39], v[38:39], v[234:235] op_sel:[0,1] op_sel_hi:[1,1]
	v_pk_mul_f32 v[40:41], v[40:41], v[234:235] op_sel:[0,1] op_sel_hi:[1,1]
	v_pk_mul_f32 v[34:35], v[34:35], v[234:235] op_sel:[0,1] op_sel_hi:[1,1]
	v_pk_mul_f32 v[36:37], v[36:37], v[234:235] op_sel:[0,1] op_sel_hi:[1,1]
	v_cvt_pk_bf16_f32 v118, v38, v39
	v_cvt_pk_bf16_f32 v119, v40, v41
	v_cvt_pk_bf16_f32 v120, v34, v35
	v_cvt_pk_bf16_f32 v121, v36, v37
	global_store_dwordx4 v143, v[118:121], s[48:49] offset:256
	v_pk_mul_f32 v[30:31], v[30:31], v[240:241] op_sel_hi:[1,0]
	v_pk_mul_f32 v[32:33], v[32:33], v[240:241] op_sel_hi:[1,0]
	v_pk_mul_f32 v[26:27], v[26:27], v[240:241] op_sel_hi:[1,0]
	v_pk_mul_f32 v[28:29], v[28:29], v[240:241] op_sel_hi:[1,0]
	v_cvt_pk_bf16_f32 v66, v30, v31
	v_cvt_pk_bf16_f32 v67, v32, v33
	v_cvt_pk_bf16_f32 v68, v26, v27
	v_cvt_pk_bf16_f32 v69, v28, v29
	global_store_dwordx4 v144, v[66:69], s[48:49]
	v_pk_mul_f32 v[22:23], v[22:23], v[240:241] op_sel_hi:[1,0]
	v_pk_mul_f32 v[24:25], v[24:25], v[240:241] op_sel_hi:[1,0]
	v_pk_mul_f32 v[18:19], v[18:19], v[240:241] op_sel_hi:[1,0]
	v_pk_mul_f32 v[20:21], v[20:21], v[240:241] op_sel_hi:[1,0]
	v_cvt_pk_bf16_f32 v78, v22, v23
	v_cvt_pk_bf16_f32 v79, v24, v25
	v_cvt_pk_bf16_f32 v80, v18, v19
	v_cvt_pk_bf16_f32 v81, v20, v21
	global_store_dwordx4 v144, v[78:81], s[48:49] offset:256
	v_pk_mul_f32 v[14:15], v[14:15], v[240:241] op_sel:[0,1] op_sel_hi:[1,1]
	v_pk_mul_f32 v[16:17], v[16:17], v[240:241] op_sel:[0,1] op_sel_hi:[1,1]
	v_pk_mul_f32 v[10:11], v[10:11], v[240:241] op_sel:[0,1] op_sel_hi:[1,1]
	v_pk_mul_f32 v[12:13], v[12:13], v[240:241] op_sel:[0,1] op_sel_hi:[1,1]
	v_cvt_pk_bf16_f32 v98, v14, v15
	v_cvt_pk_bf16_f32 v99, v16, v17
	v_cvt_pk_bf16_f32 v100, v10, v11
	v_cvt_pk_bf16_f32 v101, v12, v13
	global_store_dwordx4 v145, v[98:101], s[48:49]
	v_pk_mul_f32 v[6:7], v[6:7], v[240:241] op_sel:[0,1] op_sel_hi:[1,1]
	v_pk_mul_f32 v[8:9], v[8:9], v[240:241] op_sel:[0,1] op_sel_hi:[1,1]
	v_pk_mul_f32 v[2:3], v[2:3], v[240:241] op_sel:[0,1] op_sel_hi:[1,1]
	v_pk_mul_f32 v[4:5], v[4:5], v[240:241] op_sel:[0,1] op_sel_hi:[1,1]
	v_cvt_pk_bf16_f32 v118, v6, v7
	v_cvt_pk_bf16_f32 v119, v8, v9
	v_cvt_pk_bf16_f32 v120, v2, v3
	v_cvt_pk_bf16_f32 v121, v4, v5
	global_store_dwordx4 v145, v[118:121], s[48:49] offset:256
	s_branch .Lwin_epi_done
